# v61: v54 + P2 uses a wave-parity-flipped thread index in team 1, so the two teams' single-wave stages (block inverses, T10) run on different SIMDs
# speedup vs baseline: 1.0026x; 1.0018x over previous
; DI void fox_cumsum(const Params& P, int bh, unsigned char* smem, int tt) {
;     const int tid = tt, lane = tid & 63, wave = tid >> 6;
;     const int b = bh >> 3, hh = bh & 7;
;     float* wsum = (float*)smem;
;     const float* gates = (const float*)(P.ws + OFF_GATES);
;     const float bf = P.in[9][hh];
;     float v[8]; float run = 0.f;
; #pragma unroll
;     for (int e = 0; e < 8; ++e) {
;         const float xx = gates[((size_t)b * TSEQ + tid * 8 + e) * 16 + 8 + hh] + bf;
;         const float ls = fminf(xx, 0.f) - log1pf(__expf(-fabsf(xx)));
;         run += ls; v[e] = run;
;     }
; __global__ void __launch_bounds__(512, 2) fwd_mega(Params P) {
;     ...
;     for (int base = bid * 2; base < 1024 + 64; base += nblk * 2) {
;         PHASE_IDS
;         const int it = base + team;
;         if (it < 1024) prep_chunk(P, it, smem, tt); else fox_cumsum(P, it - 1024, smem, tt);
.LBB0_220:
	v_readlane_b32 s0, v255, 39
	v_mbcnt_lo_u32_b32 v126, -1, 0
	v_mbcnt_hi_u32_b32 v126, -1, v126
	s_nop 0
	v_and_b32_e32 v123, 63, v126
	v_add_u32_e32 v132, s0, v126
	v_lshrrev_b32_e32 v0, 2, v132
	v_and_b32_e32 v0, 64, v0
	v_xor_b32_e32 v132, v132, v0
	v_ashrrev_i32_e32 v2, 8, v132
	s_mov_b32 s0, 0x12c00
	v_mad_i32_i24 v125, v2, s0, 0
	v_add_u32_e32 v84, s86, v2
	v_subrev_u32_e32 v84, 64, v84
	v_add_u32_e32 v0, 0x440, v84
	v_cmp_gt_i32_e32 vcc, 0, v84
	s_nop 1
	v_cndmask_b32_e32 v84, v84, v0, vcc
	s_movk_i32 s0, 0x3ff
	v_and_b32_e32 v124, 0xff, v132
	v_cmp_lt_i32_e32 vcc, s0, v84
	s_and_saveexec_b64 s[0:1], vcc
	s_xor_b64 s[0:1], exec, s[0:1]
	s_cbranch_execz .LBB0_228
	v_and_b32_e32 v1, 7, v84
	v_lshlrev_b32_e32 v80, 2, v1
	global_load_dword v1, v80, s[46:47]
	v_add_u32_e32 v0, 0xfffffc00, v84
	v_lshrrev_b32_e32 v2, 3, v0
	v_mov_b32_e32 v3, v81
	v_lshl_add_u64 v[4:5], s[12:13], 0, v[80:81]
	v_lshlrev_b64 v[2:3], 17, v[2:3]
	v_lshlrev_b32_e32 v80, 9, v124
	v_lshl_add_u64 v[2:3], v[4:5], 0, v[2:3]
	v_lshl_add_u64 v[2:3], v[2:3], 0, v[80:81]
	global_load_dword v4, v[2:3], off
	global_load_dword v11, v[2:3], off offset:64
	global_load_dword v5, v[2:3], off offset:128
	global_load_dword v6, v[2:3], off offset:192
	global_load_dword v7, v[2:3], off offset:256
	global_load_dword v8, v[2:3], off offset:320
	global_load_dword v9, v[2:3], off offset:384
	global_load_dword v10, v[2:3], off offset:448
	s_movk_i32 s2, 0x80
	s_waitcnt vmcnt(7)
	v_add_f32_e32 v2, v1, v4
	v_mul_f32_e64 v4, |v2|, s92
	s_waitcnt vmcnt(6)
	v_add_f32_e32 v3, v1, v11
	v_exp_f32_e32 v4, v4
	v_mul_f32_e64 v11, |v3|, s92
	v_exp_f32_e32 v11, v11
	v_min_f32_e32 v14, 0, v2
	v_add_f32_e32 v16, 1.0, v4
	v_min_f32_e32 v15, 0, v3
	v_frexp_mant_f32_e32 v19, v16
	v_cvt_f64_f32_e32 v[2:3], v16
	v_add_f32_e32 v17, 1.0, v11
	v_add_f32_e32 v18, -1.0, v16
	v_frexp_exp_i32_f64_e32 v2, v[2:3]
	v_cmp_gt_f32_e32 vcc, s93, v19
	v_add_f32_e32 v20, -1.0, v17
	v_frexp_mant_f32_e32 v21, v17
	v_cvt_f64_f32_e32 v[12:13], v17
	v_sub_f32_e32 v22, v18, v16
	v_subbrev_co_u32_e32 v2, vcc, 0, v2, vcc
	v_sub_f32_e32 v18, v4, v18
	v_sub_f32_e32 v3, v20, v17
	v_frexp_exp_i32_f64_e32 v12, v[12:13]
	v_add_f32_e32 v13, 1.0, v22
	v_cmp_gt_f32_e32 vcc, s93, v21
	v_sub_f32_e32 v20, v11, v20
	v_add_f32_e32 v3, 1.0, v3
	v_subbrev_co_u32_e32 v12, vcc, 0, v12, vcc
	v_add_f32_e32 v13, v18, v13
	v_sub_u32_e32 v18, 0, v2
	v_cvt_f32_i32_e32 v2, v2
	v_add_f32_e32 v3, v20, v3
	v_sub_u32_e32 v19, 0, v12
	v_ldexp_f32 v16, v16, v18
	v_ldexp_f32 v13, v13, v18
	v_ldexp_f32 v17, v17, v19
	v_ldexp_f32 v3, v3, v19
	v_add_f32_e32 v18, -1.0, v16
	v_add_f32_e32 v19, 1.0, v16
	v_add_f32_e32 v20, 1.0, v18
	v_add_f32_e32 v21, -1.0, v19
	v_sub_f32_e32 v20, v16, v20
	v_sub_f32_e32 v16, v16, v21
	v_mul_f32_e32 v21, 0x3f317218, v2
	v_add_f32_e32 v20, v13, v20
	v_add_f32_e32 v13, v13, v16
	v_fma_f32 v16, v2, s94, -v21
	v_add_f32_e32 v22, v18, v20
	v_add_f32_e32 v23, v19, v13
	v_fmac_f32_e32 v16, 0xb102e308, v2
	v_sub_f32_e32 v2, v22, v18
	v_sub_f32_e32 v18, v23, v19
	v_rcp_f32_e32 v19, v23
	v_add_f32_e32 v24, v21, v16
	v_sub_f32_e32 v13, v13, v18
	v_sub_f32_e32 v18, v24, v21
	v_sub_f32_e32 v16, v16, v18
	v_mul_f32_e32 v18, v22, v19
	v_sub_f32_e32 v2, v20, v2
	v_mul_f32_e32 v20, v23, v18
	v_fma_f32 v21, v18, v23, -v20
	v_fmac_f32_e32 v21, v18, v13
	v_add_f32_e32 v25, v20, v21
	v_sub_f32_e32 v26, v22, v25
	v_sub_f32_e32 v20, v25, v20
	v_sub_f32_e32 v22, v22, v26
	v_sub_f32_e32 v20, v20, v21
	v_sub_f32_e32 v21, v22, v25
	v_add_f32_e32 v2, v2, v21
	v_add_f32_e32 v2, v20, v2
	v_add_f32_e32 v20, v26, v2
	v_mul_f32_e32 v21, v19, v20
	v_sub_f32_e32 v22, v26, v20
	v_mul_f32_e32 v25, v23, v21
	v_add_f32_e32 v2, v2, v22
	v_add_f32_e32 v22, v18, v21
	v_fma_f32 v23, v21, v23, -v25
	v_sub_f32_e32 v18, v22, v18
	v_fmac_f32_e32 v23, v21, v13
	v_sub_f32_e32 v13, v21, v18
	v_add_f32_e32 v18, v25, v23
	v_sub_f32_e32 v21, v18, v25
	v_sub_f32_e32 v25, v20, v18
	v_sub_f32_e32 v20, v20, v25
	v_sub_f32_e32 v18, v20, v18
	v_sub_f32_e32 v21, v21, v23
	v_add_f32_e32 v2, v2, v18
	v_add_f32_e32 v2, v21, v2
	v_add_f32_e32 v2, v25, v2
	v_mul_f32_e32 v2, v19, v2
	v_add_f32_e32 v2, v13, v2
	v_add_f32_e32 v13, v22, v2
	v_mul_f32_e32 v18, v13, v13
	v_fmamk_f32 v21, v18, 0x3e9b6dac, v83
	v_sub_f32_e32 v19, v13, v22
	v_ldexp_f32 v20, v13, 1
	v_mul_f32_e32 v13, v13, v18
	v_fmaak_f32 v18, v18, v21, 0x3f2aaada
	v_mul_f32_e32 v13, v13, v18
	v_add_f32_e32 v18, v20, v13
	v_sub_f32_e32 v2, v2, v19
	v_sub_f32_e32 v19, v18, v20
	v_ldexp_f32 v2, v2, 1
	v_sub_f32_e32 v13, v13, v19
	v_add_f32_e32 v2, v2, v13
	v_add_f32_e32 v13, v18, v2
	v_sub_f32_e32 v18, v13, v18
	v_add_f32_e32 v19, v24, v13
	v_sub_f32_e32 v2, v2, v18
	v_sub_f32_e32 v18, v19, v24
	v_sub_f32_e32 v20, v19, v18
	v_sub_f32_e32 v13, v13, v18
	v_add_f32_e32 v18, v16, v2
	v_sub_f32_e32 v20, v24, v20
	v_sub_f32_e32 v21, v18, v16
	v_add_f32_e32 v13, v13, v20
	v_sub_f32_e32 v20, v18, v21
	v_sub_f32_e32 v2, v2, v21
	v_sub_f32_e32 v16, v16, v20
	v_add_f32_e32 v13, v18, v13
	v_add_f32_e32 v2, v2, v16
	v_add_f32_e32 v16, v19, v13
	v_sub_f32_e32 v18, v16, v19
	v_sub_f32_e32 v13, v13, v18
	v_add_f32_e32 v2, v2, v13
	v_add_f32_e32 v2, v16, v2
	v_cmp_neq_f32_e32 vcc, s95, v4
	v_add_f32_e32 v16, 1.0, v17
	v_add_f32_e32 v18, -1.0, v16
	v_cndmask_b32_e32 v2, v112, v2, vcc
	v_cmp_ngt_f32_e32 vcc, -1.0, v4
	v_cvt_f32_i32_e32 v12, v12
	s_nop 0
	v_cndmask_b32_e32 v2, v113, v2, vcc
	v_cmp_neq_f32_e32 vcc, -1.0, v4
	s_nop 1
	v_cndmask_b32_e32 v2, v114, v2, vcc
	v_cmp_lt_f32_e64 vcc, |v4|, s84
	s_nop 1
	v_cndmask_b32_e32 v2, v2, v4, vcc
	v_add_f32_e32 v4, -1.0, v17
	v_add_f32_e32 v13, 1.0, v4
	v_sub_f32_e32 v13, v17, v13
	v_sub_f32_e32 v17, v17, v18
; DI void fox_cumsum(const Params& P, int bh, unsigned char* smem, int tt) {
;     ...
;     for (int e = 0; e < 8; ++e) {
;         const float xx = gates[((size_t)b * TSEQ + tid * 8 + e) * 16 + 8 + hh] + bf;
;         const float ls = fminf(xx, 0.f) - log1pf(__expf(-fabsf(xx)));
;         run += ls; v[e] = run;
;     }
	v_add_f32_e32 v13, v3, v13
	v_add_f32_e32 v3, v3, v17
	v_add_f32_e32 v17, v16, v3
	v_rcp_f32_e32 v18, v17
	v_sub_f32_e32 v2, v14, v2
	v_add_f32_e32 v14, v4, v13
	v_sub_f32_e32 v4, v14, v4
	v_sub_f32_e32 v4, v13, v4
	v_sub_f32_e32 v13, v17, v16
	v_sub_f32_e32 v3, v3, v13
	v_mul_f32_e32 v13, v14, v18
	v_mul_f32_e32 v16, v17, v13
	v_fma_f32 v19, v13, v17, -v16
	v_fmac_f32_e32 v19, v13, v3
	v_add_f32_e32 v20, v16, v19
	v_sub_f32_e32 v21, v14, v20
	v_sub_f32_e32 v14, v14, v21
	v_sub_f32_e32 v16, v20, v16
	v_sub_f32_e32 v14, v14, v20
	v_add_f32_e32 v4, v4, v14
	v_sub_f32_e32 v14, v16, v19
	v_add_f32_e32 v4, v14, v4
	v_add_f32_e32 v14, v21, v4
	v_mul_f32_e32 v16, v18, v14
	v_mul_f32_e32 v19, v17, v16
	v_fma_f32 v17, v16, v17, -v19
	v_fmac_f32_e32 v17, v16, v3
	v_sub_f32_e32 v3, v21, v14
	v_add_f32_e32 v3, v4, v3
	v_add_f32_e32 v4, v19, v17
	v_sub_f32_e32 v20, v14, v4
	v_sub_f32_e32 v14, v14, v20
	v_sub_f32_e32 v19, v4, v19
	v_sub_f32_e32 v4, v14, v4
	v_add_f32_e32 v3, v3, v4
	v_sub_f32_e32 v4, v19, v17
	v_add_f32_e32 v3, v4, v3
	v_add_f32_e32 v4, v13, v16
	v_add_f32_e32 v3, v20, v3
	v_sub_f32_e32 v13, v4, v13
	v_mul_f32_e32 v3, v18, v3
	v_sub_f32_e32 v13, v16, v13
	v_add_f32_e32 v3, v13, v3
	v_mul_f32_e32 v17, 0x3f317218, v12
	v_add_f32_e32 v13, v4, v3
	v_fma_f32 v18, v12, s94, -v17
	v_mul_f32_e32 v14, v13, v13
	v_fmac_f32_e32 v18, 0xb102e308, v12
	v_sub_f32_e32 v4, v13, v4
	v_fmamk_f32 v16, v14, 0x3e9b6dac, v83
	v_sub_f32_e32 v3, v3, v4
	v_add_f32_e32 v4, v17, v18
	v_fmaak_f32 v16, v14, v16, 0x3f2aaada
	v_sub_f32_e32 v12, v4, v17
	v_ldexp_f32 v17, v13, 1
	v_mul_f32_e32 v13, v13, v14
	v_mul_f32_e32 v13, v13, v16
	v_add_f32_e32 v14, v17, v13
	v_sub_f32_e32 v16, v14, v17
	v_ldexp_f32 v3, v3, 1
	v_sub_f32_e32 v13, v13, v16
	v_add_f32_e32 v3, v3, v13
	v_add_f32_e32 v13, v14, v3
	v_sub_f32_e32 v14, v13, v14
	v_sub_f32_e32 v3, v3, v14
	v_add_f32_e32 v14, v4, v13
	v_sub_f32_e32 v16, v14, v4
	v_sub_f32_e32 v17, v14, v16
	v_sub_f32_e32 v12, v18, v12
	v_sub_f32_e32 v4, v4, v17
	v_sub_f32_e32 v13, v13, v16
	v_add_f32_e32 v4, v13, v4
	v_add_f32_e32 v13, v12, v3
	v_sub_f32_e32 v16, v13, v12
	v_sub_f32_e32 v17, v13, v16
	v_sub_f32_e32 v12, v12, v17
	v_sub_f32_e32 v3, v3, v16
	v_add_f32_e32 v4, v13, v4
	v_add_f32_e32 v3, v3, v12
	v_add_f32_e32 v12, v14, v4
	v_sub_f32_e32 v13, v12, v14
	v_sub_f32_e32 v4, v4, v13
	v_add_f32_e32 v3, v3, v4
	v_add_f32_e32 v3, v12, v3
	v_cmp_neq_f32_e32 vcc, s95, v11
	s_waitcnt vmcnt(5)
	v_add_f32_e32 v4, v1, v5
	v_mul_f32_e64 v5, |v4|, s92
	v_cndmask_b32_e32 v3, v112, v3, vcc
	v_cmp_ngt_f32_e32 vcc, -1.0, v11
	v_min_f32_e32 v12, 0, v4
	v_add_f32_e32 v2, 0, v2
	v_cndmask_b32_e32 v3, v113, v3, vcc
	v_cmp_neq_f32_e32 vcc, -1.0, v11
	s_nop 1
	v_cndmask_b32_e32 v3, v114, v3, vcc
	v_cmp_lt_f32_e64 vcc, |v11|, s84
	s_nop 1
	v_cndmask_b32_e32 v3, v3, v11, vcc
	v_exp_f32_e32 v11, v5
	v_sub_f32_e32 v3, v15, v3
	v_add_f32_e32 v3, v2, v3
	v_add_f32_e32 v13, 1.0, v11
	v_add_f32_e32 v4, -1.0, v13
	v_sub_f32_e32 v5, v4, v13
	v_add_f32_e32 v5, 1.0, v5
	v_sub_f32_e32 v4, v11, v4
	v_add_f32_e32 v14, v4, v5
	v_frexp_mant_f32_e32 v15, v13
	v_cvt_f64_f32_e32 v[4:5], v13
	v_frexp_exp_i32_f64_e32 v4, v[4:5]
	v_cmp_gt_f32_e32 vcc, s93, v15
	s_nop 1
	v_subbrev_co_u32_e32 v4, vcc, 0, v4, vcc
	v_sub_u32_e32 v5, 0, v4
	v_ldexp_f32 v13, v13, v5
	v_ldexp_f32 v5, v14, v5
	v_add_f32_e32 v14, -1.0, v13
	v_add_f32_e32 v17, 1.0, v13
	v_add_f32_e32 v15, 1.0, v14
	v_add_f32_e32 v18, -1.0, v17
	v_sub_f32_e32 v15, v13, v15
	v_sub_f32_e32 v13, v13, v18
	v_add_f32_e32 v15, v5, v15
	v_add_f32_e32 v5, v5, v13
	v_add_f32_e32 v13, v17, v5
	v_rcp_f32_e32 v18, v13
	v_add_f32_e32 v16, v14, v15
	v_sub_f32_e32 v14, v16, v14
	v_sub_f32_e32 v14, v15, v14
	v_sub_f32_e32 v15, v13, v17
	v_sub_f32_e32 v5, v5, v15
	v_mul_f32_e32 v15, v16, v18
	v_mul_f32_e32 v17, v13, v15
	v_fma_f32 v19, v15, v13, -v17
	v_fmac_f32_e32 v19, v15, v5
	v_add_f32_e32 v20, v17, v19
	v_sub_f32_e32 v21, v16, v20
	v_sub_f32_e32 v16, v16, v21
	v_sub_f32_e32 v17, v20, v17
	v_sub_f32_e32 v16, v16, v20
	v_add_f32_e32 v14, v14, v16
	v_sub_f32_e32 v16, v17, v19
	v_add_f32_e32 v14, v16, v14
	v_add_f32_e32 v16, v21, v14
	v_mul_f32_e32 v17, v18, v16
	v_mul_f32_e32 v19, v13, v17
	v_fma_f32 v13, v17, v13, -v19
	v_fmac_f32_e32 v13, v17, v5
	v_sub_f32_e32 v5, v21, v16
	v_add_f32_e32 v5, v14, v5
	v_add_f32_e32 v14, v19, v13
	v_sub_f32_e32 v20, v16, v14
	v_sub_f32_e32 v16, v16, v20
	v_sub_f32_e32 v19, v14, v19
	v_sub_f32_e32 v14, v16, v14
	v_add_f32_e32 v5, v5, v14
	v_sub_f32_e32 v13, v19, v13
	v_cvt_f32_i32_e32 v4, v4
	v_add_f32_e32 v5, v13, v5
	v_add_f32_e32 v13, v15, v17
	v_add_f32_e32 v5, v20, v5
	v_sub_f32_e32 v14, v13, v15
	v_mul_f32_e32 v5, v18, v5
	v_sub_f32_e32 v14, v17, v14
	v_add_f32_e32 v5, v14, v5
	v_mul_f32_e32 v17, 0x3f317218, v4
	v_add_f32_e32 v14, v13, v5
	v_fma_f32 v18, v4, s94, -v17
	v_mul_f32_e32 v15, v14, v14
	v_fmac_f32_e32 v18, 0xb102e308, v4
	v_sub_f32_e32 v4, v14, v13
	v_fmamk_f32 v16, v15, 0x3e9b6dac, v83
	v_sub_f32_e32 v4, v5, v4
	v_add_f32_e32 v5, v17, v18
	v_fmaak_f32 v16, v15, v16, 0x3f2aaada
	v_sub_f32_e32 v13, v5, v17
	v_ldexp_f32 v17, v14, 1
	v_mul_f32_e32 v14, v14, v15
	v_mul_f32_e32 v14, v14, v16
	v_add_f32_e32 v15, v17, v14
	v_sub_f32_e32 v16, v15, v17
	v_ldexp_f32 v4, v4, 1
	v_sub_f32_e32 v14, v14, v16
	v_add_f32_e32 v4, v4, v14
	v_add_f32_e32 v14, v15, v4
	v_sub_f32_e32 v15, v14, v15
	v_sub_f32_e32 v4, v4, v15
	v_add_f32_e32 v15, v5, v14
	v_sub_f32_e32 v16, v15, v5
	v_sub_f32_e32 v17, v15, v16
	v_sub_f32_e32 v13, v18, v13
	v_sub_f32_e32 v5, v5, v17
	v_sub_f32_e32 v14, v14, v16
	v_add_f32_e32 v5, v14, v5
	v_add_f32_e32 v14, v13, v4
	v_sub_f32_e32 v16, v14, v13
	v_sub_f32_e32 v17, v14, v16
	v_sub_f32_e32 v13, v13, v17
	v_sub_f32_e32 v4, v4, v16
	v_add_f32_e32 v5, v14, v5
	v_add_f32_e32 v4, v4, v13
	v_add_f32_e32 v13, v15, v5
	v_sub_f32_e32 v14, v13, v15
	v_sub_f32_e32 v5, v5, v14
	v_add_f32_e32 v4, v4, v5
	s_waitcnt vmcnt(4)
; DI void fox_cumsum(const Params& P, int bh, unsigned char* smem, int tt) {
;     ...
;     for (int e = 0; e < 8; ++e) {
;         const float xx = gates[((size_t)b * TSEQ + tid * 8 + e) * 16 + 8 + hh] + bf;
;         const float ls = fminf(xx, 0.f) - log1pf(__expf(-fabsf(xx)));
;         run += ls; v[e] = run;
;     }
	v_add_f32_e32 v5, v1, v6
	v_mul_f32_e64 v6, |v5|, s92
	v_add_f32_e32 v4, v13, v4
	v_cmp_neq_f32_e32 vcc, s95, v11
	v_exp_f32_e32 v6, v6
	s_nop 0
	v_cndmask_b32_e32 v4, v112, v4, vcc
	v_cmp_ngt_f32_e32 vcc, -1.0, v11
	v_add_f32_e32 v13, 1.0, v6
	v_frexp_mant_f32_e32 v15, v13
	v_cndmask_b32_e32 v4, v113, v4, vcc
	v_cmp_neq_f32_e32 vcc, -1.0, v11
	s_nop 1
	v_cndmask_b32_e32 v4, v114, v4, vcc
	v_cmp_lt_f32_e64 vcc, |v11|, s84
	s_nop 1
	v_cndmask_b32_e32 v4, v4, v11, vcc
	v_sub_f32_e32 v11, v12, v4
	v_add_f32_e32 v4, -1.0, v13
	v_min_f32_e32 v12, 0, v5
	v_sub_f32_e32 v5, v4, v13
	v_add_f32_e32 v5, 1.0, v5
	v_sub_f32_e32 v4, v6, v4
	v_add_f32_e32 v14, v4, v5
	v_cvt_f64_f32_e32 v[4:5], v13
	v_frexp_exp_i32_f64_e32 v4, v[4:5]
	v_cmp_gt_f32_e32 vcc, s93, v15
	s_nop 1
	v_subbrev_co_u32_e32 v4, vcc, 0, v4, vcc
	v_sub_u32_e32 v5, 0, v4
	v_ldexp_f32 v13, v13, v5
	v_ldexp_f32 v5, v14, v5
	v_add_f32_e32 v14, -1.0, v13
	v_add_f32_e32 v17, 1.0, v13
	v_add_f32_e32 v15, 1.0, v14
	v_add_f32_e32 v18, -1.0, v17
	v_sub_f32_e32 v15, v13, v15
	v_sub_f32_e32 v13, v13, v18
	v_add_f32_e32 v15, v5, v15
	v_add_f32_e32 v5, v5, v13
	v_add_f32_e32 v13, v17, v5
	v_rcp_f32_e32 v18, v13
	v_add_f32_e32 v16, v14, v15
	v_sub_f32_e32 v14, v16, v14
	v_sub_f32_e32 v14, v15, v14
	v_sub_f32_e32 v15, v13, v17
	v_sub_f32_e32 v5, v5, v15
	v_mul_f32_e32 v15, v16, v18
	v_mul_f32_e32 v17, v13, v15
	v_fma_f32 v19, v15, v13, -v17
	v_fmac_f32_e32 v19, v15, v5
	v_add_f32_e32 v20, v17, v19
	v_sub_f32_e32 v21, v16, v20
	v_sub_f32_e32 v16, v16, v21
	v_sub_f32_e32 v17, v20, v17
	v_sub_f32_e32 v16, v16, v20
	v_add_f32_e32 v14, v14, v16
	v_sub_f32_e32 v16, v17, v19
	v_add_f32_e32 v14, v16, v14
	v_add_f32_e32 v16, v21, v14
	v_mul_f32_e32 v17, v18, v16
	v_mul_f32_e32 v19, v13, v17
	v_fma_f32 v13, v17, v13, -v19
	v_fmac_f32_e32 v13, v17, v5
	v_sub_f32_e32 v5, v21, v16
	v_add_f32_e32 v5, v14, v5
	v_add_f32_e32 v14, v19, v13
	v_sub_f32_e32 v20, v16, v14
	v_sub_f32_e32 v16, v16, v20
	v_sub_f32_e32 v19, v14, v19
	v_sub_f32_e32 v14, v16, v14
	v_add_f32_e32 v5, v5, v14
	v_sub_f32_e32 v13, v19, v13
	v_cvt_f32_i32_e32 v4, v4
	v_add_f32_e32 v5, v13, v5
	v_add_f32_e32 v13, v15, v17
	v_add_f32_e32 v5, v20, v5
	v_sub_f32_e32 v14, v13, v15
	v_mul_f32_e32 v5, v18, v5
	v_sub_f32_e32 v14, v17, v14
	v_add_f32_e32 v5, v14, v5
	v_mul_f32_e32 v17, 0x3f317218, v4
	v_add_f32_e32 v14, v13, v5
	v_fma_f32 v18, v4, s94, -v17
	v_mul_f32_e32 v15, v14, v14
	v_fmac_f32_e32 v18, 0xb102e308, v4
	v_sub_f32_e32 v4, v14, v13
	v_fmamk_f32 v16, v15, 0x3e9b6dac, v83
	v_sub_f32_e32 v4, v5, v4
	v_add_f32_e32 v5, v17, v18
	v_fmaak_f32 v16, v15, v16, 0x3f2aaada
	v_sub_f32_e32 v13, v5, v17
	v_ldexp_f32 v17, v14, 1
	v_mul_f32_e32 v14, v14, v15
	v_mul_f32_e32 v14, v14, v16
	v_add_f32_e32 v15, v17, v14
	v_sub_f32_e32 v16, v15, v17
	v_ldexp_f32 v4, v4, 1
	v_sub_f32_e32 v14, v14, v16
	v_add_f32_e32 v4, v4, v14
	v_add_f32_e32 v14, v15, v4
	v_sub_f32_e32 v15, v14, v15
	v_sub_f32_e32 v4, v4, v15
	v_add_f32_e32 v15, v5, v14
	v_sub_f32_e32 v16, v15, v5
	v_sub_f32_e32 v17, v15, v16
	v_sub_f32_e32 v13, v18, v13
	v_sub_f32_e32 v5, v5, v17
	v_sub_f32_e32 v14, v14, v16
	v_add_f32_e32 v5, v14, v5
	v_add_f32_e32 v14, v13, v4
	v_sub_f32_e32 v16, v14, v13
	v_sub_f32_e32 v17, v14, v16
	v_sub_f32_e32 v13, v13, v17
	v_sub_f32_e32 v4, v4, v16
	v_add_f32_e32 v5, v14, v5
	v_add_f32_e32 v4, v4, v13
	v_add_f32_e32 v13, v15, v5
	v_sub_f32_e32 v14, v13, v15
	v_sub_f32_e32 v5, v5, v14
	v_add_f32_e32 v4, v4, v5
	v_add_f32_e32 v4, v13, v4
	v_cmp_neq_f32_e32 vcc, s95, v6
	s_nop 1
	v_cndmask_b32_e32 v4, v112, v4, vcc
	v_cmp_ngt_f32_e32 vcc, -1.0, v6
	s_nop 1
	v_cndmask_b32_e32 v4, v113, v4, vcc
	v_cmp_neq_f32_e32 vcc, -1.0, v6
	s_nop 1
	v_cndmask_b32_e32 v4, v114, v4, vcc
	v_cmp_lt_f32_e64 vcc, |v6|, s84
	s_nop 1
	v_cndmask_b32_e32 v4, v4, v6, vcc
	s_waitcnt vmcnt(3)
	v_add_f32_e32 v6, v1, v7
	v_sub_f32_e32 v5, v12, v4
	v_mul_f32_e64 v4, |v6|, s92
	v_exp_f32_e32 v12, v4
	v_add_f32_e32 v4, v3, v11
	v_min_f32_e32 v11, 0, v6
	v_add_f32_e32 v5, v4, v5
	v_add_f32_e32 v13, 1.0, v12
	v_add_f32_e32 v6, -1.0, v13
	v_sub_f32_e32 v7, v6, v13
	v_add_f32_e32 v7, 1.0, v7
	v_sub_f32_e32 v6, v12, v6
	v_add_f32_e32 v14, v6, v7
	v_frexp_mant_f32_e32 v15, v13
	v_cvt_f64_f32_e32 v[6:7], v13
	v_frexp_exp_i32_f64_e32 v6, v[6:7]
	v_cmp_gt_f32_e32 vcc, s93, v15
	s_nop 1
	v_subbrev_co_u32_e32 v6, vcc, 0, v6, vcc
	v_sub_u32_e32 v7, 0, v6
	v_ldexp_f32 v13, v13, v7
	v_ldexp_f32 v7, v14, v7
	v_add_f32_e32 v14, -1.0, v13
	v_add_f32_e32 v17, 1.0, v13
	v_add_f32_e32 v15, 1.0, v14
	v_add_f32_e32 v18, -1.0, v17
	v_sub_f32_e32 v15, v13, v15
	v_sub_f32_e32 v13, v13, v18
	v_add_f32_e32 v15, v7, v15
	v_add_f32_e32 v7, v7, v13
	v_add_f32_e32 v13, v17, v7
	v_rcp_f32_e32 v18, v13
	v_add_f32_e32 v16, v14, v15
	v_sub_f32_e32 v14, v16, v14
	v_sub_f32_e32 v14, v15, v14
	v_sub_f32_e32 v15, v13, v17
	v_sub_f32_e32 v7, v7, v15
	v_mul_f32_e32 v15, v16, v18
	v_mul_f32_e32 v17, v13, v15
	v_fma_f32 v19, v15, v13, -v17
	v_fmac_f32_e32 v19, v15, v7
	v_add_f32_e32 v20, v17, v19
	v_sub_f32_e32 v21, v16, v20
	v_sub_f32_e32 v16, v16, v21
	v_sub_f32_e32 v17, v20, v17
	v_sub_f32_e32 v16, v16, v20
	v_add_f32_e32 v14, v14, v16
	v_sub_f32_e32 v16, v17, v19
	v_add_f32_e32 v14, v16, v14
	v_add_f32_e32 v16, v21, v14
	v_mul_f32_e32 v17, v18, v16
	v_mul_f32_e32 v19, v13, v17
	v_fma_f32 v13, v17, v13, -v19
	v_fmac_f32_e32 v13, v17, v7
	v_sub_f32_e32 v7, v21, v16
	v_add_f32_e32 v7, v14, v7
	v_add_f32_e32 v14, v19, v13
	v_sub_f32_e32 v20, v16, v14
	v_sub_f32_e32 v16, v16, v20
	v_sub_f32_e32 v19, v14, v19
	v_sub_f32_e32 v14, v16, v14
	v_add_f32_e32 v7, v7, v14
	v_sub_f32_e32 v13, v19, v13
	v_cvt_f32_i32_e32 v6, v6
	v_add_f32_e32 v7, v13, v7
	v_add_f32_e32 v13, v15, v17
	v_add_f32_e32 v7, v20, v7
	v_sub_f32_e32 v14, v13, v15
	v_mul_f32_e32 v7, v18, v7
	v_sub_f32_e32 v14, v17, v14
	v_add_f32_e32 v7, v14, v7
	v_mul_f32_e32 v17, 0x3f317218, v6
	v_add_f32_e32 v14, v13, v7
	v_fma_f32 v18, v6, s94, -v17
	v_mul_f32_e32 v15, v14, v14
	v_fmac_f32_e32 v18, 0xb102e308, v6
	v_sub_f32_e32 v6, v14, v13
	v_fmamk_f32 v16, v15, 0x3e9b6dac, v83
	v_sub_f32_e32 v6, v7, v6
	v_add_f32_e32 v7, v17, v18
	v_fmaak_f32 v16, v15, v16, 0x3f2aaada
	v_sub_f32_e32 v13, v7, v17
	v_ldexp_f32 v17, v14, 1
	v_mul_f32_e32 v14, v14, v15
	v_mul_f32_e32 v14, v14, v16
	v_add_f32_e32 v15, v17, v14
	v_sub_f32_e32 v16, v15, v17
	v_ldexp_f32 v6, v6, 1
	v_sub_f32_e32 v14, v14, v16
	v_add_f32_e32 v6, v6, v14
	v_add_f32_e32 v14, v15, v6
	v_sub_f32_e32 v15, v14, v15
	v_sub_f32_e32 v6, v6, v15
	v_add_f32_e32 v15, v7, v14
	v_sub_f32_e32 v16, v15, v7
	v_sub_f32_e32 v17, v15, v16
	v_sub_f32_e32 v13, v18, v13
	v_sub_f32_e32 v7, v7, v17
	v_sub_f32_e32 v14, v14, v16
	v_add_f32_e32 v7, v14, v7
	v_add_f32_e32 v14, v13, v6
	v_sub_f32_e32 v16, v14, v13
	v_sub_f32_e32 v17, v14, v16
	v_sub_f32_e32 v13, v13, v17
	v_sub_f32_e32 v6, v6, v16
	v_add_f32_e32 v7, v14, v7
	v_add_f32_e32 v6, v6, v13
	v_add_f32_e32 v13, v15, v7
	v_sub_f32_e32 v14, v13, v15
	v_sub_f32_e32 v7, v7, v14
	v_add_f32_e32 v6, v6, v7
	s_waitcnt vmcnt(2)
; DI void fox_cumsum(const Params& P, int bh, unsigned char* smem, int tt) {
;     ...
;     for (int e = 0; e < 8; ++e) {
;         const float xx = gates[((size_t)b * TSEQ + tid * 8 + e) * 16 + 8 + hh] + bf;
;         const float ls = fminf(xx, 0.f) - log1pf(__expf(-fabsf(xx)));
;         run += ls; v[e] = run;
;     }
	v_add_f32_e32 v7, v1, v8
	v_mul_f32_e64 v8, |v7|, s92
	v_add_f32_e32 v6, v13, v6
	v_cmp_neq_f32_e32 vcc, s95, v12
	v_exp_f32_e32 v8, v8
	s_nop 0
	v_cndmask_b32_e32 v6, v112, v6, vcc
	v_cmp_ngt_f32_e32 vcc, -1.0, v12
	v_add_f32_e32 v13, 1.0, v8
	v_frexp_mant_f32_e32 v15, v13
	v_cndmask_b32_e32 v6, v113, v6, vcc
	v_cmp_neq_f32_e32 vcc, -1.0, v12
	s_nop 1
	v_cndmask_b32_e32 v6, v114, v6, vcc
	v_cmp_lt_f32_e64 vcc, |v12|, s84
	s_nop 1
	v_cndmask_b32_e32 v6, v6, v12, vcc
	v_sub_f32_e32 v11, v11, v6
	v_add_f32_e32 v6, -1.0, v13
	v_min_f32_e32 v12, 0, v7
	v_sub_f32_e32 v7, v6, v13
	v_add_f32_e32 v7, 1.0, v7
	v_sub_f32_e32 v6, v8, v6
	v_add_f32_e32 v14, v6, v7
	v_cvt_f64_f32_e32 v[6:7], v13
	v_frexp_exp_i32_f64_e32 v6, v[6:7]
	v_cmp_gt_f32_e32 vcc, s93, v15
	s_nop 1
	v_subbrev_co_u32_e32 v6, vcc, 0, v6, vcc
	v_sub_u32_e32 v7, 0, v6
	v_ldexp_f32 v13, v13, v7
	v_ldexp_f32 v7, v14, v7
	v_add_f32_e32 v14, -1.0, v13
	v_add_f32_e32 v17, 1.0, v13
	v_add_f32_e32 v15, 1.0, v14
	v_add_f32_e32 v18, -1.0, v17
	v_sub_f32_e32 v15, v13, v15
	v_sub_f32_e32 v13, v13, v18
	v_add_f32_e32 v15, v7, v15
	v_add_f32_e32 v7, v7, v13
	v_add_f32_e32 v13, v17, v7
	v_rcp_f32_e32 v18, v13
	v_add_f32_e32 v16, v14, v15
	v_sub_f32_e32 v14, v16, v14
	v_sub_f32_e32 v14, v15, v14
	v_sub_f32_e32 v15, v13, v17
	v_sub_f32_e32 v7, v7, v15
	v_mul_f32_e32 v15, v16, v18
	v_mul_f32_e32 v17, v13, v15
	v_fma_f32 v19, v15, v13, -v17
	v_fmac_f32_e32 v19, v15, v7
	v_add_f32_e32 v20, v17, v19
	v_sub_f32_e32 v21, v16, v20
	v_sub_f32_e32 v16, v16, v21
	v_sub_f32_e32 v17, v20, v17
	v_sub_f32_e32 v16, v16, v20
	v_add_f32_e32 v14, v14, v16
	v_sub_f32_e32 v16, v17, v19
	v_add_f32_e32 v14, v16, v14
	v_add_f32_e32 v16, v21, v14
	v_mul_f32_e32 v17, v18, v16
	v_mul_f32_e32 v19, v13, v17
	v_fma_f32 v13, v17, v13, -v19
	v_fmac_f32_e32 v13, v17, v7
	v_sub_f32_e32 v7, v21, v16
	v_add_f32_e32 v7, v14, v7
	v_add_f32_e32 v14, v19, v13
	v_sub_f32_e32 v20, v16, v14
	v_sub_f32_e32 v16, v16, v20
	v_sub_f32_e32 v19, v14, v19
	v_sub_f32_e32 v14, v16, v14
	v_add_f32_e32 v7, v7, v14
	v_sub_f32_e32 v13, v19, v13
	v_cvt_f32_i32_e32 v6, v6
	v_add_f32_e32 v7, v13, v7
	v_add_f32_e32 v13, v15, v17
	v_add_f32_e32 v7, v20, v7
	v_sub_f32_e32 v14, v13, v15
	v_mul_f32_e32 v7, v18, v7
	v_sub_f32_e32 v14, v17, v14
	v_add_f32_e32 v7, v14, v7
	v_mul_f32_e32 v17, 0x3f317218, v6
	v_add_f32_e32 v14, v13, v7
	v_fma_f32 v18, v6, s94, -v17
	v_mul_f32_e32 v15, v14, v14
	v_fmac_f32_e32 v18, 0xb102e308, v6
	v_sub_f32_e32 v6, v14, v13
	v_fmamk_f32 v16, v15, 0x3e9b6dac, v83
	v_sub_f32_e32 v6, v7, v6
	v_add_f32_e32 v7, v17, v18
	v_fmaak_f32 v16, v15, v16, 0x3f2aaada
	v_sub_f32_e32 v13, v7, v17
	v_ldexp_f32 v17, v14, 1
	v_mul_f32_e32 v14, v14, v15
	v_mul_f32_e32 v14, v14, v16
	v_add_f32_e32 v15, v17, v14
	v_sub_f32_e32 v16, v15, v17
	v_ldexp_f32 v6, v6, 1
	v_sub_f32_e32 v14, v14, v16
	v_add_f32_e32 v6, v6, v14
	v_add_f32_e32 v14, v15, v6
	v_sub_f32_e32 v15, v14, v15
	v_sub_f32_e32 v6, v6, v15
	v_add_f32_e32 v15, v7, v14
	v_sub_f32_e32 v16, v15, v7
	v_sub_f32_e32 v17, v15, v16
	v_sub_f32_e32 v13, v18, v13
	v_sub_f32_e32 v7, v7, v17
	v_sub_f32_e32 v14, v14, v16
	v_add_f32_e32 v7, v14, v7
	v_add_f32_e32 v14, v13, v6
	v_sub_f32_e32 v16, v14, v13
	v_sub_f32_e32 v17, v14, v16
	v_sub_f32_e32 v13, v13, v17
	v_sub_f32_e32 v6, v6, v16
	v_add_f32_e32 v7, v14, v7
	v_add_f32_e32 v6, v6, v13
	v_add_f32_e32 v13, v15, v7
	v_sub_f32_e32 v14, v13, v15
	v_sub_f32_e32 v7, v7, v14
	v_add_f32_e32 v6, v6, v7
	v_add_f32_e32 v6, v13, v6
	v_cmp_neq_f32_e32 vcc, s95, v8
	s_nop 1
	v_cndmask_b32_e32 v6, v112, v6, vcc
	v_cmp_ngt_f32_e32 vcc, -1.0, v8
	s_nop 1
	v_cndmask_b32_e32 v6, v113, v6, vcc
	v_cmp_neq_f32_e32 vcc, -1.0, v8
	s_nop 1
	v_cndmask_b32_e32 v6, v114, v6, vcc
	v_cmp_lt_f32_e64 vcc, |v8|, s84
	s_nop 1
	v_cndmask_b32_e32 v6, v6, v8, vcc
	s_waitcnt vmcnt(1)
	v_add_f32_e32 v8, v1, v9
	v_sub_f32_e32 v7, v12, v6
	v_mul_f32_e64 v6, |v8|, s92
	v_exp_f32_e32 v12, v6
	v_add_f32_e32 v6, v5, v11
	v_min_f32_e32 v11, 0, v8
	s_waitcnt vmcnt(0)
	v_add_f32_e32 v1, v1, v10
	v_add_f32_e32 v13, 1.0, v12
	v_add_f32_e32 v8, -1.0, v13
	v_sub_f32_e32 v9, v8, v13
	v_add_f32_e32 v9, 1.0, v9
	v_sub_f32_e32 v8, v12, v8
	v_add_f32_e32 v14, v8, v9
	v_frexp_mant_f32_e32 v15, v13
	v_cvt_f64_f32_e32 v[8:9], v13
	v_frexp_exp_i32_f64_e32 v8, v[8:9]
	v_cmp_gt_f32_e32 vcc, s93, v15
	v_add_f32_e32 v7, v6, v7
	s_nop 0
	v_subbrev_co_u32_e32 v8, vcc, 0, v8, vcc
	v_sub_u32_e32 v9, 0, v8
	v_ldexp_f32 v13, v13, v9
	v_ldexp_f32 v9, v14, v9
	v_add_f32_e32 v14, -1.0, v13
	v_add_f32_e32 v17, 1.0, v13
	v_add_f32_e32 v15, 1.0, v14
	v_add_f32_e32 v18, -1.0, v17
	v_sub_f32_e32 v15, v13, v15
	v_sub_f32_e32 v13, v13, v18
	v_add_f32_e32 v15, v9, v15
	v_add_f32_e32 v9, v9, v13
	v_add_f32_e32 v13, v17, v9
	v_rcp_f32_e32 v18, v13
	v_add_f32_e32 v16, v14, v15
	v_sub_f32_e32 v14, v16, v14
	v_sub_f32_e32 v14, v15, v14
	v_sub_f32_e32 v15, v13, v17
	v_sub_f32_e32 v9, v9, v15
	v_mul_f32_e32 v15, v16, v18
	v_mul_f32_e32 v17, v13, v15
	v_fma_f32 v19, v15, v13, -v17
	v_fmac_f32_e32 v19, v15, v9
	v_add_f32_e32 v20, v17, v19
	v_sub_f32_e32 v21, v16, v20
	v_sub_f32_e32 v16, v16, v21
	v_sub_f32_e32 v17, v20, v17
	v_sub_f32_e32 v16, v16, v20
	v_add_f32_e32 v14, v14, v16
	v_sub_f32_e32 v16, v17, v19
	v_add_f32_e32 v14, v16, v14
	v_add_f32_e32 v16, v21, v14
	v_mul_f32_e32 v17, v18, v16
	v_mul_f32_e32 v19, v13, v17
	v_fma_f32 v13, v17, v13, -v19
	v_fmac_f32_e32 v13, v17, v9
	v_sub_f32_e32 v9, v21, v16
	v_add_f32_e32 v9, v14, v9
	v_add_f32_e32 v14, v19, v13
	v_sub_f32_e32 v20, v16, v14
	v_sub_f32_e32 v16, v16, v20
	v_sub_f32_e32 v19, v14, v19
	v_sub_f32_e32 v14, v16, v14
	v_add_f32_e32 v9, v9, v14
	v_sub_f32_e32 v13, v19, v13
; DI float shup(float v, int o, int lane) { return __int_as_float(__builtin_amdgcn_ds_bpermute(((lane - o) & 63) << 2, __float_as_int(v))); }
; DI void fox_cumsum(const Params& P, int bh, unsigned char* smem, int tt) {
;     ...
;     for (int e = 0; e < 8; ++e) {
;         const float xx = gates[((size_t)b * TSEQ + tid * 8 + e) * 16 + 8 + hh] + bf;
;         const float ls = fminf(xx, 0.f) - log1pf(__expf(-fabsf(xx)));
;         run += ls; v[e] = run;
;     }
;     float sc = run;
; #pragma unroll
;     for (int o = 1; o < 64; o <<= 1) { const float t = shup(sc, o, lane); if (lane >= o) sc += t; }
;     if (lane == 63) wsum[wave] = sc;
;     __syncthreads();
;     float off = sc - run;
;     for (int w = 0; w < wave; ++w) off += wsum[w];
	v_cvt_f32_i32_e32 v8, v8
	v_add_f32_e32 v9, v13, v9
	v_add_f32_e32 v13, v15, v17
	v_add_f32_e32 v9, v20, v9
	v_sub_f32_e32 v14, v13, v15
	v_mul_f32_e32 v9, v18, v9
	v_sub_f32_e32 v14, v17, v14
	v_add_f32_e32 v9, v14, v9
	v_mul_f32_e32 v17, 0x3f317218, v8
	v_add_f32_e32 v14, v13, v9
	v_fma_f32 v18, v8, s94, -v17
	v_mul_f32_e32 v15, v14, v14
	v_fmac_f32_e32 v18, 0xb102e308, v8
	v_sub_f32_e32 v8, v14, v13
	v_fmamk_f32 v16, v15, 0x3e9b6dac, v83
	v_sub_f32_e32 v8, v9, v8
	v_add_f32_e32 v9, v17, v18
	v_fmaak_f32 v16, v15, v16, 0x3f2aaada
	v_sub_f32_e32 v13, v9, v17
	v_ldexp_f32 v17, v14, 1
	v_mul_f32_e32 v14, v14, v15
	v_mul_f32_e32 v14, v14, v16
	v_add_f32_e32 v15, v17, v14
	v_sub_f32_e32 v16, v15, v17
	v_ldexp_f32 v8, v8, 1
	v_sub_f32_e32 v14, v14, v16
	v_add_f32_e32 v8, v8, v14
	v_add_f32_e32 v14, v15, v8
	v_sub_f32_e32 v15, v14, v15
	v_sub_f32_e32 v8, v8, v15
	v_add_f32_e32 v15, v9, v14
	v_sub_f32_e32 v16, v15, v9
	v_sub_f32_e32 v17, v15, v16
	v_sub_f32_e32 v13, v18, v13
	v_sub_f32_e32 v9, v9, v17
	v_sub_f32_e32 v14, v14, v16
	v_add_f32_e32 v9, v14, v9
	v_add_f32_e32 v14, v13, v8
	v_sub_f32_e32 v16, v14, v13
	v_sub_f32_e32 v17, v14, v16
	v_sub_f32_e32 v13, v13, v17
	v_sub_f32_e32 v8, v8, v16
	v_add_f32_e32 v9, v14, v9
	v_add_f32_e32 v8, v8, v13
	v_add_f32_e32 v13, v15, v9
	v_sub_f32_e32 v14, v13, v15
	v_sub_f32_e32 v9, v9, v14
	v_add_f32_e32 v8, v8, v9
	v_mul_f32_e64 v9, |v1|, s92
	v_add_f32_e32 v8, v13, v8
	v_cmp_neq_f32_e32 vcc, s95, v12
	v_exp_f32_e32 v10, v9
	v_min_f32_e32 v1, 0, v1
	v_cndmask_b32_e32 v8, v112, v8, vcc
	v_cmp_ngt_f32_e32 vcc, -1.0, v12
	s_nop 1
	v_cndmask_b32_e32 v8, v113, v8, vcc
	v_cmp_neq_f32_e32 vcc, -1.0, v12
	s_nop 1
	v_cndmask_b32_e32 v8, v114, v8, vcc
	v_cmp_lt_f32_e64 vcc, |v12|, s84
	s_nop 1
	v_cndmask_b32_e32 v8, v8, v12, vcc
	v_add_f32_e32 v12, 1.0, v10
	v_sub_f32_e32 v11, v11, v8
	v_add_f32_e32 v8, -1.0, v12
	v_sub_f32_e32 v9, v8, v12
	v_add_f32_e32 v9, 1.0, v9
	v_sub_f32_e32 v8, v10, v8
	v_add_f32_e32 v13, v8, v9
	v_frexp_mant_f32_e32 v14, v12
	v_cvt_f64_f32_e32 v[8:9], v12
	v_frexp_exp_i32_f64_e32 v8, v[8:9]
	v_cmp_gt_f32_e32 vcc, s93, v14
	s_nop 1
	v_subbrev_co_u32_e32 v8, vcc, 0, v8, vcc
	v_sub_u32_e32 v9, 0, v8
	v_ldexp_f32 v12, v12, v9
	v_ldexp_f32 v9, v13, v9
	v_add_f32_e32 v13, -1.0, v12
	v_add_f32_e32 v16, 1.0, v12
	v_add_f32_e32 v14, 1.0, v13
	v_add_f32_e32 v17, -1.0, v16
	v_sub_f32_e32 v14, v12, v14
	v_sub_f32_e32 v12, v12, v17
	v_add_f32_e32 v14, v9, v14
	v_add_f32_e32 v9, v9, v12
	v_add_f32_e32 v12, v16, v9
	v_rcp_f32_e32 v17, v12
	v_add_f32_e32 v15, v13, v14
	v_sub_f32_e32 v13, v15, v13
	v_sub_f32_e32 v13, v14, v13
	v_sub_f32_e32 v14, v12, v16
	v_sub_f32_e32 v9, v9, v14
	v_mul_f32_e32 v14, v15, v17
	v_mul_f32_e32 v16, v12, v14
	v_fma_f32 v18, v14, v12, -v16
	v_fmac_f32_e32 v18, v14, v9
	v_add_f32_e32 v19, v16, v18
	v_sub_f32_e32 v20, v15, v19
	v_sub_f32_e32 v15, v15, v20
	v_sub_f32_e32 v16, v19, v16
	v_sub_f32_e32 v15, v15, v19
	v_add_f32_e32 v13, v13, v15
	v_sub_f32_e32 v15, v16, v18
	v_add_f32_e32 v13, v15, v13
	v_add_f32_e32 v15, v20, v13
	v_mul_f32_e32 v16, v17, v15
	v_mul_f32_e32 v18, v12, v16
	v_fma_f32 v12, v16, v12, -v18
	v_fmac_f32_e32 v12, v16, v9
	v_sub_f32_e32 v9, v20, v15
	v_add_f32_e32 v9, v13, v9
	v_add_f32_e32 v13, v18, v12
	v_sub_f32_e32 v19, v15, v13
	v_sub_f32_e32 v15, v15, v19
	v_sub_f32_e32 v18, v13, v18
	v_sub_f32_e32 v13, v15, v13
	v_add_f32_e32 v9, v9, v13
	v_sub_f32_e32 v12, v18, v12
	v_cvt_f32_i32_e32 v8, v8
	v_add_f32_e32 v9, v12, v9
	v_add_f32_e32 v12, v14, v16
	v_add_f32_e32 v9, v19, v9
	v_sub_f32_e32 v13, v12, v14
	v_mul_f32_e32 v9, v17, v9
	v_sub_f32_e32 v13, v16, v13
	v_add_f32_e32 v9, v13, v9
	v_mul_f32_e32 v16, 0x3f317218, v8
	v_add_f32_e32 v13, v12, v9
	v_fma_f32 v17, v8, s94, -v16
	v_mul_f32_e32 v14, v13, v13
	v_fmac_f32_e32 v17, 0xb102e308, v8
	v_sub_f32_e32 v8, v13, v12
	v_fmamk_f32 v15, v14, 0x3e9b6dac, v83
	v_sub_f32_e32 v8, v9, v8
	v_add_f32_e32 v9, v16, v17
	v_fmaak_f32 v15, v14, v15, 0x3f2aaada
	v_sub_f32_e32 v12, v9, v16
	v_ldexp_f32 v16, v13, 1
	v_mul_f32_e32 v13, v13, v14
	v_mul_f32_e32 v13, v13, v15
	v_add_f32_e32 v14, v16, v13
	v_sub_f32_e32 v15, v14, v16
	v_ldexp_f32 v8, v8, 1
	v_sub_f32_e32 v13, v13, v15
	v_add_f32_e32 v8, v8, v13
	v_add_f32_e32 v13, v14, v8
	v_sub_f32_e32 v14, v13, v14
	v_sub_f32_e32 v8, v8, v14
	v_add_f32_e32 v14, v9, v13
	v_sub_f32_e32 v15, v14, v9
	v_sub_f32_e32 v16, v14, v15
	v_sub_f32_e32 v12, v17, v12
	v_sub_f32_e32 v9, v9, v16
	v_sub_f32_e32 v13, v13, v15
	v_add_f32_e32 v9, v13, v9
	v_add_f32_e32 v13, v12, v8
	v_sub_f32_e32 v15, v13, v12
	v_sub_f32_e32 v16, v13, v15
	v_sub_f32_e32 v12, v12, v16
	v_sub_f32_e32 v8, v8, v15
	v_add_f32_e32 v9, v13, v9
	v_add_f32_e32 v8, v8, v12
	v_add_f32_e32 v12, v14, v9
	v_sub_f32_e32 v13, v12, v14
	v_sub_f32_e32 v9, v9, v13
	v_add_f32_e32 v8, v8, v9
	v_add_f32_e32 v8, v12, v8
	v_cmp_neq_f32_e32 vcc, s95, v10
	s_nop 1
	v_cndmask_b32_e32 v8, v112, v8, vcc
	v_cmp_ngt_f32_e32 vcc, -1.0, v10
	s_nop 1
	v_cndmask_b32_e32 v8, v113, v8, vcc
	v_cmp_neq_f32_e32 vcc, -1.0, v10
	s_nop 1
	v_cndmask_b32_e32 v8, v114, v8, vcc
	v_cmp_lt_f32_e64 vcc, |v10|, s84
	s_nop 1
	v_cndmask_b32_e32 v8, v8, v10, vcc
	v_sub_f32_e32 v1, v1, v8
	v_add_f32_e32 v8, v7, v11
	v_add_f32_e32 v9, v8, v1
	v_lshlrev_b32_e32 v1, 2, v124
	v_add_u32_e32 v10, 0xfc, v1
	v_and_b32_e32 v10, 0xfc, v10
	ds_bpermute_b32 v10, v10, v9
	v_cmp_eq_u32_e32 vcc, 0, v123
	v_add_u32_e32 v11, 0xf8, v1
	v_and_b32_e32 v11, 0xfc, v11
	s_waitcnt lgkmcnt(0)
	v_add_f32_e32 v10, v9, v10
	v_cndmask_b32_e32 v10, v10, v9, vcc
	ds_bpermute_b32 v11, v11, v10
	v_cmp_gt_u32_e32 vcc, 2, v123
	s_waitcnt lgkmcnt(0)
	v_add_f32_e32 v11, v10, v11
	v_cndmask_b32_e32 v10, v11, v10, vcc
	v_add_u32_e32 v11, 0xf0, v1
	v_and_b32_e32 v11, 0xfc, v11
	ds_bpermute_b32 v11, v11, v10
	v_cmp_gt_u32_e32 vcc, 4, v123
	s_waitcnt lgkmcnt(0)
	v_add_f32_e32 v11, v10, v11
	v_cndmask_b32_e32 v10, v11, v10, vcc
	v_add_u32_e32 v11, 0xe0, v1
	v_and_b32_e32 v11, 0xfc, v11
	ds_bpermute_b32 v11, v11, v10
	v_cmp_gt_u32_e32 vcc, 8, v123
	s_waitcnt lgkmcnt(0)
	v_add_f32_e32 v11, v10, v11
	v_cndmask_b32_e32 v10, v11, v10, vcc
	v_add_u32_e32 v11, 0xc0, v1
	v_and_b32_e32 v11, 0xfc, v11
	ds_bpermute_b32 v11, v11, v10
	v_cmp_gt_u32_e32 vcc, 16, v123
	v_bitop3_b32 v1, v1, s2, v115 bitop3:0x6c
	s_waitcnt lgkmcnt(0)
	v_add_f32_e32 v11, v10, v11
	v_cndmask_b32_e32 v10, v11, v10, vcc
	ds_bpermute_b32 v1, v1, v10
	v_cmp_eq_u32_e32 vcc, 63, v123
	s_waitcnt lgkmcnt(0)
	v_add_f32_e32 v11, v10, v1
	v_lshrrev_b32_e32 v1, 6, v124
	s_and_saveexec_b64 s[2:3], vcc
	v_lshl_add_u32 v12, v1, 2, v125
	ds_write_b32 v12, v11
	s_or_b64 exec, exec, s[2:3]
	v_cmp_gt_u32_e32 vcc, 32, v123
	s_waitcnt lgkmcnt(0)
	s_barrier
	v_cndmask_b32_e32 v10, v11, v10, vcc
	v_sub_f32_e32 v10, v10, v9
	v_cmp_lt_u32_e32 vcc, 63, v124
	s_and_saveexec_b64 s[2:3], vcc
	s_cbranch_execz .LBB0_227
	v_lshlrev_b32_e32 v1, 2, v1
	s_mov_b64 s[4:5], 0
